# work-queue pop prefetch: next ticket atomic issued right after a successful pop (v253/v254), on top of the stack
# baseline (speedup 1.0000x reference)
; __global__ void __launch_bounds__(512) hybrid_fwd(Params p) {
;     ...
;       const int q0 = (int)((unsigned)__builtin_amdgcn_s_getreg((3 << 11) | 20) & 7u);
; #pragma unroll 1
;       for (int qi = 0; qi < 8; ++qi) {
;         const int bq = (q0 + qi) & 7;
; #pragma unroll 1
;         for (;;) {
;           if (tid == 0) *slot = (int)atomicAdd(ctl + l * 8 + bq, 1u);
.LBB0_335:
	v_mov_b32_e32 v254, 0
	v_writelane_b32 v251, s3, 62
	s_and_b32 s0, s3, 7
	s_lshl_b32 s54, s0, 13
	s_mul_i32 s8, s0, 0x4400000
	v_readlane_b32 s0, v251, 59
	s_add_i32 s0, s1, s0
	v_writelane_b32 v251, s1, 63
	s_and_b32 s2, s0, 7
	s_lshl_b32 s0, s2, 2
	v_readlane_b32 s1, v251, 56
	s_add_u32 s6, s1, s0
	v_readlane_b32 s0, v251, 57
	s_addc_u32 s7, s0, 0
	s_lshl_b32 s0, s2, 13
	v_writelane_b32 v250, s6, 0
	s_lshl_b32 s3, s2, 20
	s_mul_i32 s2, s2, 0x4400000
	v_writelane_b32 v250, s7, 1
	v_readlane_b32 s6, v252, 49
	v_readlane_b32 s7, v252, 50
	s_add_u32 s6, s6, s3
	s_addc_u32 s7, s7, 0
	s_add_u32 s55, s56, s2
	s_addc_u32 s87, s57, 0
	v_writelane_b32 v250, s6, 2
	s_add_u32 s93, s55, 0x1380
	s_addc_u32 s2, s87, 0
	v_writelane_b32 v250, s7, 3
	v_writelane_b32 v250, s2, 4
	s_add_u32 s2, s55, 0x1580
	v_writelane_b32 v250, s2, 5
	s_addc_u32 s2, s87, 0
	s_mov_b32 s9, s91
	v_writelane_b32 v250, s2, 6
	v_readlane_b32 s2, v251, 38
	v_writelane_b32 v250, s8, 7
	s_add_u32 s6, s2, s8
	v_readlane_b32 s2, v251, 39
	v_writelane_b32 v250, s9, 8
	s_addc_u32 s7, s2, 0
	v_writelane_b32 v250, s6, 9
	s_mov_b32 s1, s91
	s_nop 0
	v_writelane_b32 v250, s7, 10
	v_writelane_b32 v250, s54, 11
	v_writelane_b32 v250, s55, 12
	v_writelane_b32 v250, s87, 13
	v_writelane_b32 v250, s93, 14
	s_branch .LBB0_339

; __global__ void __launch_bounds__(512) hybrid_fwd(Params p) {
;     ...
;         for (;;) {
;           if (tid == 0) *slot = (int)atomicAdd(ctl + l * 8 + bq, 1u);
;           __syncthreads();
;           const int idx = *slot;
.LBB0_339:
	s_mov_b64 s[6:7], exec
	v_readlane_b32 s2, v251, 44
	v_readlane_b32 s3, v251, 45
	s_and_b64 s[2:3], s[6:7], s[2:3]
	s_mov_b64 exec, s[2:3]
	s_cbranch_execz .LBB0_343
	s_mov_b64 s[10:11], exec
	v_mbcnt_lo_u32_b32 v0, s10, 0
	v_mbcnt_hi_u32_b32 v0, s11, v0
	v_cmp_eq_u32_e32 vcc, 0, v0
	s_and_saveexec_b64 s[8:9], vcc
	s_cbranch_execz .LBB0_342
	v_readfirstlane_b32 s2, v254
	s_cmp_eq_u32 s2, 0
	s_cbranch_scc0 .Lmy_pop_pref
	s_bcnt1_i32_b64 s2, s[10:11]
	v_mov_b32_e32 v2, s2
	v_readlane_b32 s2, v250, 0
	v_readlane_b32 s3, v250, 1
	s_nop 4
	global_atomic_add v2, v1, v2, s[2:3] sc0
	s_branch .LBB0_342
.Lmy_pop_pref:
	s_waitcnt vmcnt(0)
	v_mov_b32_e32 v2, v253

; #define LAS __attribute__((address_space(3)))
; template <int MODE>
; DI void dense_unit(const Params& p, int l, int b, int n, LAS unsigned char* lds) {
;     ...
;   bf16x8 qf[4];
; #pragma unroll
;   for (int s = 0; s < 4; ++s) qf[s] = *(const bf16x8*)(proj + tq * NP + QCOL + hd * 64 + 16 * s + 8 * h);
;   LAS int* flag = (LAS int*)(lds + D_FLAG);
;   const int ntiles = n + 1;
;   u32x4 kr[4], vr[4];
;   {
;     const int m0 = (MODE == 2) ? n : 0; const u16* base = proj + ((size_t)b * S + m0 * 64) * NP;
; #pragma unroll
;     for (int i = 0; i < 4; ++i) { const int c = tid + 512 * i, row = c >> 5, c16 = c & 31; kr[i] = *(const u32x4*)(base + (size_t)row * NP + KCOL + c16 * 8); vr[i] = *(const u32x4*)(base + (size_t)row * NP + VCOL + c16 * 8); }
; #pragma unroll
;     for (int i = 0; i < 4; ++i) { const int c = tid + 512 * i, row = c >> 5, c16 = c & 31; *(LAS u32x4*)(lds + D_KOFF + row * D_RS + c16 * 16) = kr[i]; *(LAS u32x4*)(lds + D_VOFF + row * D_RS + c16 * 16) = vr[i]; }
; __global__ void __launch_bounds__(512) hybrid_fwd(Params p) {
;     ...
;           if (tid == 0) *slot = (int)atomicAdd(ctl + l * 8 + bq, 1u);
;           __syncthreads();
;           const int idx = *slot;
;           __syncthreads();
;           if (idx >= MIX_UNITS_B) break;
;           if (idx < 4) ret_scan_unit(p, l, bq, idx, lds);
;           else if (idx < 132) dense256_unit<0>(p, l, bq, 31 - ((idx - 4) & 31), (idx - 4) >> 5, lds);
;           else if (idx < 388) dsa_unit(p, l, bq, 255 - (idx - 132), lds);
;           else dense_unit<2>(p, l, bq, 127 - (idx - 388), lds);
.LBB0_343:
	s_or_b64 exec, exec, s[6:7]
	v_mov_b32_e32 v0, s79
	s_waitcnt lgkmcnt(0)
	s_barrier
	ds_read_b32 v0, v0
	s_movk_i32 s2, 0x203
	s_mov_b64 s[6:7], -1
	s_waitcnt lgkmcnt(0)
	s_barrier
	v_cmp_lt_i32_e32 vcc, s2, v0
	v_readfirstlane_b32 s78, v0
	s_cbranch_vccnz .LBB0_338
	v_readlane_b32 s2, v251, 44
	v_readlane_b32 s3, v251, 45
	v_mov_b32_e32 v254, 1
	s_and_saveexec_b64 s[8:9], s[2:3]
	s_cbranch_execz .Lmy_pf_skip
	v_mov_b32_e32 v253, 1
	v_readlane_b32 s2, v250, 0
	v_readlane_b32 s3, v250, 1
	s_nop 4
	global_atomic_add v253, v1, v253, s[2:3] sc0
.Lmy_pf_skip:
	s_or_b64 exec, exec, s[8:9]
	s_cmp_gt_i32 s78, 3
	s_cbranch_scc0 .LBB0_978
	s_cmpk_gt_u32 s78, 0x83
	s_cbranch_scc0 .LBB0_964
	s_cmpk_gt_u32 s78, 0x183
	s_cbranch_scc0 .LBB0_362
	s_sub_i32 s79, 0x203, s78
	v_mov_b32_e32 v4, v168
	s_lshl_b32 s2, s79, 6
	v_and_b32_e32 v3, 31, v4
	v_lshrrev_b32_e32 v0, 1, v4
	s_add_i32 s6, s2, s0
	v_and_or_b32 v2, v0, 32, v3
	v_ashrrev_i32_e32 v0, 1, v4
	v_or_b32_e32 v114, s6, v2
	v_mov_b64_e32 v[6:7], s[56:57]
	s_waitcnt vmcnt(5)
	v_and_b32_e32 v100, 0xffffffc0, v0
	v_bfe_u32 v5, v4, 5, 1
	s_waitcnt vmcnt(4)
	v_mad_u64_u32 v[98:99], s[2:3], v114, s85, v[6:7]
	v_ashrrev_i32_e32 v101, 31, v100
	v_lshl_add_u64 v[6:7], v[100:101], 1, v[98:99]
	v_lshlrev_b32_e32 v0, 4, v5
	v_lshl_add_u64 v[6:7], v[6:7], 0, v[0:1]
	s_mov_b64 s[2:3], 0x1980
	s_movk_i32 s7, 0x1000
	s_mulk_i32 s6, 0x2200
	v_lshl_add_u64 v[8:9], v[6:7], 0, s[2:3]
	v_add_co_u32_e32 v6, vcc, s7, v6
	s_add_u32 s2, s56, s6
	s_nop 0
	v_addc_co_u32_e32 v7, vcc, 0, v7, vcc
	s_addc_u32 s3, s57, 0
	v_lshlrev_b32_e32 v0, 3, v4
	global_load_dwordx4 v[50:53], v[6:7], off offset:2432
	global_load_dwordx4 v[54:57], v[8:9], off offset:32
	global_load_dwordx4 v[58:61], v[8:9], off offset:64
	global_load_dwordx4 v[62:65], v[8:9], off offset:96
	v_and_b32_e32 v0, 0xf8, v0
	v_ashrrev_i32_e32 v6, 5, v4
	v_mov_b64_e32 v[10:11], s[2:3]
	v_mad_i64_i32 v[8:9], s[2:3], v6, s85, v[10:11]
	v_lshlrev_b32_e32 v0, 1, v0
	v_lshl_add_u64 v[8:9], v[8:9], 0, v[0:1]
	v_add_co_u32_e32 v8, vcc, s7, v8
	v_add_u32_e32 v7, 0x200, v4
	s_nop 0
	v_addc_co_u32_e32 v9, vcc, 0, v9, vcc
	v_ashrrev_i32_e32 v7, 5, v7
	global_load_dwordx4 v[66:69], v[8:9], off offset:2944
	global_load_dwordx4 v[70:73], v[8:9], off offset:3456
	v_mad_i64_i32 v[8:9], s[2:3], v7, s85, v[10:11]
	v_lshl_add_u64 v[8:9], v[8:9], 0, v[0:1]
	v_add_co_u32_e32 v8, vcc, s7, v8
	v_writelane_b32 v250, s90, 15
	s_nop 0
	v_addc_co_u32_e32 v9, vcc, 0, v9, vcc
	global_load_dwordx4 v[74:77], v[8:9], off offset:2944
	global_load_dwordx4 v[78:81], v[8:9], off offset:3456
	v_add_u32_e32 v8, 0x400, v4
	v_ashrrev_i32_e32 v8, 5, v8
	v_mad_i64_i32 v[12:13], s[2:3], v8, s85, v[10:11]
	v_add_u32_e32 v9, 0x600, v4
	v_lshl_add_u64 v[12:13], v[12:13], 0, v[0:1]
	v_ashrrev_i32_e32 v9, 5, v9
	v_add_co_u32_e32 v12, vcc, s7, v12
	v_mad_i64_i32 v[10:11], s[2:3], v9, s85, v[10:11]
	s_nop 0
	v_addc_co_u32_e32 v13, vcc, 0, v13, vcc
	v_lshl_add_u64 v[10:11], v[10:11], 0, v[0:1]
	global_load_dwordx4 v[82:85], v[12:13], off offset:2944
	global_load_dwordx4 v[86:89], v[12:13], off offset:3456
	v_add_co_u32_e32 v10, vcc, s7, v10
	s_movk_i32 s2, 0x210
	s_nop 0
	v_addc_co_u32_e32 v11, vcc, 0, v11, vcc
	global_load_dwordx4 v[90:93], v[10:11], off offset:2944
	global_load_dwordx4 v[94:97], v[10:11], off offset:3456
	v_lshlrev_b32_e32 v10, 4, v4
	v_and_b32_e32 v10, 0x1f0, v10
	v_add_u32_e32 v101, 0, v10
	v_mul_lo_u32 v116, v6, s2
	v_add_u32_e32 v115, s80, v10
	v_add_u32_e32 v10, v101, v116
	v_mul_lo_u32 v117, v7, s2
	v_mul_lo_u32 v118, v8, s2
	v_mul_lo_u32 v119, v9, s2
	s_movk_i32 s94, 0x1000
	v_cmp_gt_i32_e32 vcc, 3, v4
	v_writelane_b32 v250, s91, 16
	s_waitcnt vmcnt(7)
	ds_write_b128 v10, v[66:69]
	v_add_u32_e32 v10, v115, v116
	s_waitcnt vmcnt(6)
	ds_write_b128 v10, v[70:73]
	v_add_u32_e32 v10, v101, v117
	s_waitcnt vmcnt(5)
	ds_write_b128 v10, v[74:77]
	v_add_u32_e32 v10, v115, v117
	s_waitcnt vmcnt(4)
	ds_write_b128 v10, v[78:81]
	v_add_u32_e32 v10, v101, v118
	s_waitcnt vmcnt(3)
; #define LAS __attribute__((address_space(3)))
; DI f32x16 zero16() { f32x16 z; for (int i = 0; i < 16; ++i) z[i] = 0.f; return z; }
; template <int MODE>
; DI void dense_unit(const Params& p, int l, int b, int n, LAS unsigned char* lds) {
;     ...
;     for (int i = 0; i < 4; ++i) { const int c = tid + 512 * i, row = c >> 5, c16 = c & 31; *(LAS u32x4*)(lds + D_KOFF + row * D_RS + c16 * 16) = kr[i]; *(LAS u32x4*)(lds + D_VOFF + row * D_RS + c16 * 16) = vr[i]; }
;     if (tid < 3) flag[tid] = 0;
;   }
;   __syncthreads();
;   f32x16 o1[2] = {zero16(), zero16()}, o2[2] = {zero16(), zero16()};
;   float l1 = 0.f, l2 = 0.f, carry = 1.0f;
;   const float lg2g = log2f(1.0f - exp2f(-5.0f - (float)hd));
;   const float cd = exp2f(lg2g * 64.0f);
;   (void)l2; (void)carry; (void)cd; (void)lg2g; (void)iq;
; #pragma unroll 1
;   for (int it = 0; it < ntiles; ++it) {
	ds_write_b128 v10, v[82:85]
	v_add_u32_e32 v10, v115, v118
	s_waitcnt vmcnt(2)
	ds_write_b128 v10, v[86:89]
	v_add_u32_e32 v10, v101, v119
	s_waitcnt vmcnt(1)
	ds_write_b128 v10, v[90:93]
	v_add_u32_e32 v10, v115, v119
	s_waitcnt vmcnt(0)
	ds_write_b128 v10, v[94:97]
	s_and_saveexec_b64 s[6:7], vcc
	v_lshl_add_u32 v10, v4, 2, 0
	v_add_u32_e32 v10, 0x21000, v10
	ds_write_b32 v10, v1
	s_mov_b64 s[90:91], s[56:57]
	s_or_b64 exec, exec, s[6:7]
	v_lshlrev_b32_e32 v120, 2, v5
	v_and_b32_e32 v10, 63, v4
	v_mad_i64_i32 v[102:103], s[2:3], v6, s85, 0
	v_mad_i64_i32 v[104:105], s[2:3], v7, s85, 0
	v_mad_i64_i32 v[106:107], s[2:3], v8, s85, 0
	v_and_b32_e32 v6, 0xffffff80, v4
	v_lshl_add_u32 v7, v5, 4, 0
	v_lshrrev_b32_e32 v5, 2, v4
	v_and_b32_e32 v8, 16, v4
	v_cmp_eq_u32_e64 s[10:11], 0, v4
	v_or_b32_e32 v4, 32, v120
	v_cmp_lt_u32_e64 s[12:13], v4, v2
	v_or_b32_e32 v4, 33, v120
	v_cmp_lt_u32_e64 s[14:15], v4, v2
	v_or_b32_e32 v4, 34, v120
	v_cmp_lt_u32_e64 s[16:17], v4, v2
	v_or_b32_e32 v4, 35, v120
	v_cmp_lt_u32_e64 s[18:19], v4, v2
	v_or_b32_e32 v4, 40, v120
	v_cmp_lt_u32_e64 s[20:21], v4, v2
	v_or_b32_e32 v4, 41, v120
	v_mad_i64_i32 v[108:109], s[2:3], v9, s85, 0
	v_lshlrev_b32_e32 v9, 2, v10
	v_cmp_lt_u32_e64 s[22:23], v4, v2
	v_or_b32_e32 v4, 42, v120
	v_and_b32_e32 v9, 12, v9
	v_cmp_lt_u32_e64 s[24:25], v4, v2
	v_or_b32_e32 v4, 43, v120
	v_or3_b32 v8, v8, v9, v100
	v_cmp_lt_u32_e64 s[26:27], v4, v2
	v_or_b32_e32 v4, 48, v120
	v_cmp_lt_u32_e64 s[28:29], v4, v2
	v_lshlrev_b32_e32 v4, 1, v8
	v_or_b32_e32 v8, 1, v120
	v_cmp_lt_u32_e64 s[48:49], v8, v2
	v_or_b32_e32 v8, 2, v120
	v_cmp_lt_u32_e64 s[50:51], v8, v2
	v_or_b32_e32 v8, 3, v120
	v_cmp_lt_u32_e64 s[52:53], v8, v2
	v_or_b32_e32 v8, 8, v120
	v_cmp_lt_u32_e64 s[54:55], v8, v2
	v_or_b32_e32 v8, 9, v120
	v_cmp_lt_u32_e64 s[56:57], v8, v2
	v_or_b32_e32 v8, 10, v120
	v_cmp_lt_u32_e64 s[58:59], v8, v2
	v_or_b32_e32 v8, 11, v120
	v_cmp_lt_u32_e64 s[60:61], v8, v2
	v_or_b32_e32 v8, 16, v120
	v_cmp_lt_u32_e64 s[62:63], v8, v2
	v_or_b32_e32 v8, 17, v120
	v_cmp_lt_u32_e64 s[64:65], v8, v2
	v_or_b32_e32 v8, 18, v120
	v_cmp_lt_u32_e64 s[66:67], v8, v2
	v_or_b32_e32 v8, 19, v120
	v_cmp_lt_u32_e64 s[68:69], v8, v2
	v_or_b32_e32 v8, 24, v120
	v_cmp_lt_u32_e64 s[70:71], v8, v2
	v_or_b32_e32 v8, 25, v120
	v_and_or_b32 v5, v5, 3, v120
	v_cmp_lt_u32_e64 s[72:73], v8, v2
	v_or_b32_e32 v8, 26, v120
	v_cmp_gt_u32_e64 s[6:7], 32, v10
	v_cmp_eq_u32_e64 s[8:9], 0, v10
	v_mul_u32_u24_e32 v3, 0x210, v3
	v_or_b32_e32 v9, 56, v120
	v_or_b32_e32 v10, 49, v120
	v_or_b32_e32 v11, 57, v120
	v_or_b32_e32 v12, 50, v120
	v_or_b32_e32 v13, 58, v120
	v_or_b32_e32 v14, 51, v120
	v_or_b32_e32 v15, 59, v120
	v_mul_u32_u24_e32 v5, 0x210, v5
	v_cmp_lt_u32_e64 s[74:75], v8, v2
	v_or_b32_e32 v8, 27, v120
	v_mov_b32_e32 v18, v1
	v_mov_b32_e32 v19, v1
	v_cmp_lt_u32_e64 s[30:31], v9, v2
	v_cmp_lt_u32_e64 s[34:35], v10, v2
	v_cmp_lt_u32_e64 s[36:37], v11, v2
	v_cmp_lt_u32_e64 s[38:39], v12, v2
	v_cmp_lt_u32_e64 s[40:41], v13, v2
	v_cmp_lt_u32_e64 s[42:43], v14, v2
	v_cmp_lt_u32_e64 s[44:45], v15, v2
	v_cmp_lt_u32_e64 s[46:47], v120, v2
	v_cmp_lt_u32_e64 s[76:77], v8, v2
	v_add3_u32 v121, v7, v6, v3
	v_add3_u32 v123, s80, v5, v4
	s_lshl_b32 s2, s78, 6
	v_mov_b32_e32 v20, v1
	v_mov_b32_e32 v21, v1
	v_mov_b32_e32 v22, v1
	v_mov_b32_e32 v23, v1
	v_mov_b32_e32 v24, v1
	v_mov_b32_e32 v25, v1
	v_mov_b32_e32 v26, v1
	v_mov_b32_e32 v27, v1
	v_mov_b32_e32 v28, v1
	v_mov_b32_e32 v29, v1
	v_mov_b32_e32 v30, v1
	v_mov_b32_e32 v31, v1
	v_mov_b32_e32 v32, v1
	v_mov_b32_e32 v33, v1
	v_mov_b64_e32 v[2:3], v[18:19]
	s_mov_b32 s84, 0
	s_sub_i32 s86, 0x204, s78
	s_mov_b32 s87, 1
	s_add_i32 s80, 0, 0x21000
	s_sub_i32 s93, 0x8080, s2
	v_mov_b32_e32 v110, 1.0
	v_readlane_b32 s81, v251, 41
	v_mov_b64_e32 v[4:5], v[20:21]
	v_mov_b64_e32 v[6:7], v[22:23]
	v_mov_b64_e32 v[8:9], v[24:25]
	v_mov_b64_e32 v[10:11], v[26:27]
	v_mov_b64_e32 v[12:13], v[28:29]
	v_mov_b64_e32 v[14:15], v[30:31]
	v_mov_b64_e32 v[16:17], v[32:33]
	s_waitcnt lgkmcnt(0)
	s_barrier
	s_branch .LBB0_351

; __global__ void __launch_bounds__(512) hybrid_fwd(Params p) {
	.amdhsa_kernel _Z10hybrid_fwd6Params
		.amdhsa_group_segment_fixed_size 0
		.amdhsa_private_segment_fixed_size 0
		.amdhsa_kernarg_size 408
		.amdhsa_user_sgpr_count 2
		.amdhsa_user_sgpr_dispatch_ptr 0
		.amdhsa_user_sgpr_queue_ptr 0
		.amdhsa_user_sgpr_kernarg_segment_ptr 1
		.amdhsa_user_sgpr_dispatch_id 0
		.amdhsa_user_sgpr_kernarg_preload_length 0
		.amdhsa_user_sgpr_kernarg_preload_offset 0
		.amdhsa_user_sgpr_private_segment_size 0
		.amdhsa_uses_dynamic_stack 0
		.amdhsa_enable_private_segment 0
		.amdhsa_system_sgpr_workgroup_id_x 1
		.amdhsa_system_sgpr_workgroup_id_y 0
		.amdhsa_system_sgpr_workgroup_id_z 0
		.amdhsa_system_sgpr_workgroup_info 0
		.amdhsa_system_vgpr_workitem_id 2
		.amdhsa_next_free_vgpr 256
		.amdhsa_next_free_sgpr 102
		.amdhsa_accum_offset 256
		.amdhsa_reserve_vcc 1
		.amdhsa_float_round_mode_32 0
		.amdhsa_float_round_mode_16_64 0
		.amdhsa_float_denorm_mode_32 3
		.amdhsa_float_denorm_mode_16_64 3
		.amdhsa_dx10_clamp 1
		.amdhsa_ieee_mode 1
		.amdhsa_fp16_overflow 0
		.amdhsa_tg_split 0
		.amdhsa_exception_fp_ieee_invalid_op 0
		.amdhsa_exception_fp_denorm_src 0
		.amdhsa_exception_fp_ieee_div_zero 0
		.amdhsa_exception_fp_ieee_overflow 0
		.amdhsa_exception_fp_ieee_underflow 0
		.amdhsa_exception_fp_ieee_inexact 0
		.amdhsa_exception_int_div_zero 0
	.end_amdhsa_kernel

; __global__ void __launch_bounds__(512) hybrid_fwd(Params p) {
amdhsa.kernels:
  - .agpr_count:     0
    .args:
      - .offset:         0
        .size:           152
        .value_kind:     by_value
      - .offset:         152
        .size:           4
        .value_kind:     hidden_block_count_x
      - .offset:         156
        .size:           4
        .value_kind:     hidden_block_count_y
      - .offset:         160
        .size:           4
        .value_kind:     hidden_block_count_z
      - .offset:         164
        .size:           2
        .value_kind:     hidden_group_size_x
      - .offset:         166
        .size:           2
        .value_kind:     hidden_group_size_y
      - .offset:         168
        .size:           2
        .value_kind:     hidden_group_size_z
      - .offset:         170
        .size:           2
        .value_kind:     hidden_remainder_x
      - .offset:         172
        .size:           2
        .value_kind:     hidden_remainder_y
      - .offset:         174
        .size:           2
        .value_kind:     hidden_remainder_z
      - .offset:         192
        .size:           8
        .value_kind:     hidden_global_offset_x
      - .offset:         200
        .size:           8
        .value_kind:     hidden_global_offset_y
      - .offset:         208
        .size:           8
        .value_kind:     hidden_global_offset_z
      - .offset:         216
        .size:           2
        .value_kind:     hidden_grid_dims
      - .offset:         240
        .size:           8
        .value_kind:     hidden_multigrid_sync_arg
      - .offset:         272
        .size:           4
        .value_kind:     hidden_dynamic_lds_size
    .group_segment_fixed_size: 0
    .kernarg_segment_align: 8
    .kernarg_segment_size: 408
    .language:       OpenCL C
    .language_version:
      - 2
      - 0
    .max_flat_workgroup_size: 512
    .name:           _Z10hybrid_fwd6Params
    .private_segment_fixed_size: 0
    .sgpr_count:     108
    .sgpr_spill_count: 146
    .symbol:         _Z10hybrid_fwd6Params.kd
    .uniform_work_group_size: 1
    .uses_dynamic_stack: false
    .vgpr_count:     256
    .vgpr_spill_count: 0
    .wavefront_size: 64
